# scan loop counted waits + split-K LDS-reduced gemm tails (phases 4,5)
# speedup vs baseline: 1.0201x; 1.0201x over previous
.LBB0_874:
	s_or_b64 exec, exec, s[52:53]
	ds_read_b128 v[214:217], v183 offset:44032
	ds_read_b128 v[218:221], v183 offset:48640
	s_cmp_lg_u32 s70, 0
	s_cbranch_scc1 .Lmy_scan_w10
	s_waitcnt vmcnt(10)
.Lmy_scan_w10:
	v_pk_mul_f32 v[14:15], v[14:15], v[120:121] op_sel_hi:[1,0]
	v_pk_mul_f32 v[12:13], v[12:13], v[120:121] op_sel_hi:[1,0]
	v_pk_mul_f32 v[10:11], v[10:11], v[120:121] op_sel_hi:[1,0]
	v_pk_mul_f32 v[8:9], v[8:9], v[120:121] op_sel_hi:[1,0]
	v_pk_mul_f32 v[6:7], v[6:7], v[120:121] op_sel_hi:[1,0]
	v_pk_mul_f32 v[4:5], v[4:5], v[120:121] op_sel_hi:[1,0]
	v_pk_mul_f32 v[2:3], v[2:3], v[120:121] op_sel_hi:[1,0]
	v_pk_mul_f32 v[0:1], v[0:1], v[120:121] op_sel_hi:[1,0]
	v_pk_mul_f32 v[30:31], v[30:31], v[120:121] op_sel_hi:[1,0]
	v_pk_mul_f32 v[28:29], v[28:29], v[120:121] op_sel_hi:[1,0]
	v_pk_mul_f32 v[26:27], v[26:27], v[120:121] op_sel_hi:[1,0]
	v_pk_mul_f32 v[24:25], v[24:25], v[120:121] op_sel_hi:[1,0]
	v_pk_mul_f32 v[22:23], v[22:23], v[120:121] op_sel_hi:[1,0]
	v_pk_mul_f32 v[20:21], v[20:21], v[120:121] op_sel_hi:[1,0]
	v_pk_mul_f32 v[18:19], v[18:19], v[120:121] op_sel_hi:[1,0]
	v_pk_mul_f32 v[16:17], v[16:17], v[120:121] op_sel_hi:[1,0]
	s_waitcnt lgkmcnt(1)
	v_mfma_f32_32x32x16_bf16 v[0:15], v[214:217], v[116:119], v[0:15]
	ds_read_b128 v[120:123], v208 offset:32
	s_waitcnt lgkmcnt(1)
	v_mfma_f32_32x32x16_bf16 v[16:31], v[218:221], v[116:119], v[16:31]
	s_and_saveexec_b64 s[34:35], s[14:15]
	s_xor_b64 s[52:53], exec, s[34:35]
	s_andn2_saveexec_b64 s[52:53], s[52:53]
	s_cbranch_execz .LBB0_876
	ds_read_b128 v[116:119], v184 offset:34848
	ds_read_b128 v[214:217], v184 offset:39456
	s_waitcnt lgkmcnt(1)
	v_mfma_f32_32x32x16_bf16 v[32:47], v[116:119], v[120:123], v[32:47]
	s_waitcnt lgkmcnt(0)
	v_mfma_f32_32x32x16_bf16 v[48:63], v[214:217], v[120:123], v[48:63]

.LBB0_880:
	s_or_b64 exec, exec, s[52:53]
	ds_read_b128 v[116:119], v183 offset:44128
	ds_read_b128 v[214:217], v183 offset:48736
	s_and_b64 vcc, exec, s[50:51]
	s_waitcnt lgkmcnt(1)
	v_mfma_f32_32x32x16_bf16 v[0:15], v[116:119], v[120:123], v[0:15]
	s_waitcnt lgkmcnt(0)
	v_mfma_f32_32x32x16_bf16 v[16:31], v[214:217], v[120:123], v[16:31]
	s_cbranch_vccz .LBB0_899
	s_cmp_lg_u64 s[10:11], 0
	s_cbranch_scc1 .Lmy_scan_fa0
	s_waitcnt vmcnt(9)
	ds_write_b128 v129, v[80:83]
	s_waitcnt vmcnt(8)
	ds_write_b128 v173, v[84:87]
	s_waitcnt vmcnt(7)
	ds_write_b128 v174, v[92:95]
	s_waitcnt vmcnt(6)
	ds_write_b128 v175, v[104:107]
	s_branch .Lmy_scan_faj
.Lmy_scan_fa0:
	s_waitcnt vmcnt(17)
	ds_write_b128 v129, v[80:83]
	s_waitcnt vmcnt(16)
	ds_write_b128 v173, v[84:87]
	s_waitcnt vmcnt(15)
	ds_write_b128 v174, v[92:95]
	s_waitcnt vmcnt(14)
	ds_write_b128 v175, v[104:107]
.Lmy_scan_faj:
	s_cmp_lt_u32 s70, 30
	s_cbranch_scc0 .LBB0_899
	s_and_saveexec_b64 s[34:35], s[16:17]
	s_xor_b64 s[52:53], exec, s[34:35]
	v_add3_u32 v80, v151, s47, 64
	v_mad_i64_i32 v[80:81], s[34:35], v80, s60, v[126:127]
	s_or_saveexec_b64 s[52:53], s[52:53]
	s_ashr_i32 s49, s48, 31
	s_lshl_b64 s[34:35], s[48:49], 14
	v_lshl_add_u64 v[104:105], v[158:159], 0, s[34:35]
	s_xor_b64 exec, exec, s[52:53]
	v_lshl_add_u64 v[80:81], v[104:105], 0, v[152:153]
	s_or_b64 exec, exec, s[52:53]
	global_load_dwordx4 v[80:83], v[80:81], off
	s_and_saveexec_b64 s[34:35], s[4:5]
	s_xor_b64 s[52:53], exec, s[34:35]
	v_add3_u32 v84, v172, s47, 64
	v_mad_i64_i32 v[84:85], s[34:35], v84, s60, v[126:127]
	s_andn2_saveexec_b64 s[52:53], s[52:53]
	v_lshl_add_u64 v[84:85], v[104:105], 0, v[154:155]
	s_or_b64 exec, exec, s[52:53]
	global_load_dwordx4 v[84:87], v[84:85], off
	s_and_saveexec_b64 s[34:35], s[6:7]
	s_xor_b64 s[52:53], exec, s[34:35]
	v_add_u32_e32 v92, s47, v204
	v_mad_i64_i32 v[92:93], s[34:35], v92, s60, v[126:127]
	s_andn2_saveexec_b64 s[52:53], s[52:53]
	v_lshl_add_u64 v[92:93], v[104:105], 0, v[156:157]
	s_or_b64 exec, exec, s[52:53]
	global_load_dwordx4 v[92:95], v[92:93], off
	s_and_saveexec_b64 s[34:35], s[8:9]
	s_xor_b64 s[52:53], exec, s[34:35]
	v_add_u32_e32 v104, s47, v203
	v_mad_i64_i32 v[106:107], s[34:35], v104, s60, v[126:127]
	s_andn2_saveexec_b64 s[52:53], s[52:53]
	v_lshl_add_u64 v[106:107], v[104:105], 0, v[146:147]
	s_or_b64 exec, exec, s[52:53]
	global_load_dwordx4 v[104:107], v[106:107], off

.LBB0_901:
	s_or_b64 exec, exec, s[52:53]
	s_waitcnt lgkmcnt(0)
	s_barrier
	ds_read_b128 v[32:35], v206
	ds_read_b128 v[36:39], v206 offset:16
	ds_read_b128 v[40:43], v206 offset:32
	ds_read_b128 v[44:47], v206 offset:48
	s_waitcnt lgkmcnt(3)
	v_pk_mul_f32 v[48:49], v[34:35], v[34:35]
	v_pk_mul_f32 v[50:51], v[32:33], v[32:33]
	s_nop 0
	v_pk_mov_b32 v[52:53], v[50:51], v[48:49] op_sel:[1,0]
	v_mov_b32_e32 v51, v49
	v_pk_add_f32 v[48:49], v[52:53], v[50:51]
	s_waitcnt lgkmcnt(2)
	v_pk_mul_f32 v[50:51], v[38:39], v[38:39]
	v_pk_mul_f32 v[52:53], v[36:37], v[36:37]
	v_pk_add_f32 v[48:49], v[48:49], v[48:49] op_sel:[0,1] op_sel_hi:[1,0]
	v_pk_mov_b32 v[54:55], v[52:53], v[50:51] op_sel:[1,0]
	v_mov_b32_e32 v53, v51
	v_pk_add_f32 v[50:51], v[54:55], v[52:53]
	s_waitcnt lgkmcnt(0)
	v_mul_f32_e32 v52, v44, v44
	v_mul_f32_e32 v53, v45, v45
	v_pk_add_f32 v[50:51], v[50:51], v[50:51] op_sel:[0,1] op_sel_hi:[1,0]
	v_mov_b32_e32 v49, v52
	v_mov_b32_e32 v51, v53
	v_pk_add_f32 v[48:49], v[48:49], v[50:51]
	v_mul_f32_e32 v50, v41, v41
	v_mul_f32_e32 v52, v43, v43
	v_mul_f32_e32 v54, v46, v46
	v_mul_f32_e32 v55, v47, v47
	v_pk_fma_f32 v[50:51], v[40:41], v[40:41], v[50:51] op_sel_hi:[1,1,0]
	v_pk_fma_f32 v[52:53], v[42:43], v[42:43], v[52:53] op_sel_hi:[1,1,0]
	v_mov_b32_e32 v51, v54
	v_mov_b32_e32 v53, v55
	v_pk_add_f32 v[50:51], v[50:51], v[52:53]
	s_nop 0
	v_pk_add_f32 v[48:49], v[48:49], v[50:51]
	v_and_b32_e32 v50, 64, v149
	v_add_f32_e32 v48, v48, v49
	v_xor_b32_e32 v49, 1, v149
	v_add_u32_e32 v50, 64, v50
	v_cmp_lt_i32_e32 vcc, v49, v50
	s_cmp_lt_u32 s70, 30
	s_cbranch_scc1 .Lmy_scan_w4
	s_waitcnt vmcnt(0)
	s_branch .Lmy_scan_wj
.Lmy_scan_w4:
	s_waitcnt vmcnt(4)
.Lmy_scan_wj:
	v_and_b32_e32 v51, 0xffff0000, v112
	v_cndmask_b32_e32 v49, v149, v49, vcc
	v_lshlrev_b32_e32 v49, 2, v49
	ds_bpermute_b32 v49, v49, v48
	s_waitcnt lgkmcnt(0)
	v_add_f32_e32 v48, v48, v49
	v_xor_b32_e32 v49, 2, v149
	v_cmp_lt_i32_e32 vcc, v49, v50
	s_nop 1
	v_cndmask_b32_e32 v49, v149, v49, vcc
	v_lshlrev_b32_e32 v49, 2, v49
	ds_bpermute_b32 v49, v49, v48
	s_waitcnt lgkmcnt(0)
	v_add_f32_e32 v48, v48, v49
	v_xor_b32_e32 v49, 4, v149
	v_cmp_lt_i32_e32 vcc, v49, v50
	v_lshlrev_b32_e32 v50, 16, v112
	s_nop 0
	v_cndmask_b32_e32 v49, v149, v49, vcc
	v_lshlrev_b32_e32 v49, 2, v49
	ds_bpermute_b32 v49, v49, v48
	s_waitcnt lgkmcnt(0)
	v_add_f32_e32 v48, v48, v49
	v_fmamk_f32 v48, v48, 0x3c000000, v171
	v_mul_f32_e32 v49, 0x4b800000, v48
	v_cmp_gt_f32_e32 vcc, s68, v48
	s_nop 1
	v_cndmask_b32_e32 v48, v48, v49, vcc
	v_rsq_f32_e32 v48, v48
	s_nop 0
	v_mul_f32_e32 v49, 0x45800000, v48
	v_cndmask_b32_e32 v48, v48, v49, vcc
	v_pk_mul_f32 v[32:33], v[32:33], v[48:49] op_sel_hi:[1,0]
	v_pk_mul_f32 v[34:35], v[34:35], v[48:49] op_sel_hi:[1,0]
	v_pk_mul_f32 v[32:33], v[76:77], v[32:33]
	v_pk_mul_f32 v[34:35], v[78:79], v[34:35]
	v_pk_mul_f32 v[32:33], v[32:33], v[50:51]
	v_lshlrev_b32_e32 v50, 16, v113
	v_and_b32_e32 v51, 0xffff0000, v113
	v_pk_mul_f32 v[36:37], v[36:37], v[48:49] op_sel_hi:[1,0]
	v_pk_mul_f32 v[34:35], v[34:35], v[50:51]
	v_lshlrev_b32_e32 v50, 16, v114
	v_and_b32_e32 v51, 0xffff0000, v114
	v_pk_mul_f32 v[36:37], v[72:73], v[36:37]
	v_pk_mul_f32 v[38:39], v[38:39], v[48:49] op_sel_hi:[1,0]
	v_pk_mul_f32 v[36:37], v[36:37], v[50:51]
	v_lshlrev_b32_e32 v50, 16, v115
	v_and_b32_e32 v51, 0xffff0000, v115
	v_pk_mul_f32 v[38:39], v[74:75], v[38:39]
	v_pk_mul_f32 v[40:41], v[40:41], v[48:49] op_sel_hi:[1,0]
	v_pk_mul_f32 v[38:39], v[38:39], v[50:51]
	v_lshlrev_b32_e32 v50, 16, v108
	v_and_b32_e32 v51, 0xffff0000, v108
	v_pk_mul_f32 v[40:41], v[68:69], v[40:41]
	v_pk_mul_f32 v[42:43], v[42:43], v[48:49] op_sel_hi:[1,0]
	v_pk_mul_f32 v[40:41], v[40:41], v[50:51]
	v_lshlrev_b32_e32 v50, 16, v109
	v_and_b32_e32 v51, 0xffff0000, v109
	v_pk_mul_f32 v[42:43], v[70:71], v[42:43]
	v_pk_mul_f32 v[44:45], v[44:45], v[48:49] op_sel_hi:[1,0]
	v_pk_mul_f32 v[42:43], v[42:43], v[50:51]
	v_lshlrev_b32_e32 v50, 16, v110
	v_and_b32_e32 v51, 0xffff0000, v110
	v_pk_mul_f32 v[44:45], v[64:65], v[44:45]
	v_pk_mul_f32 v[46:47], v[46:47], v[48:49] op_sel_hi:[1,0]
	v_lshl_add_u64 v[48:49], v[166:167], 0, v[164:165]
	v_pk_mul_f32 v[44:45], v[44:45], v[50:51]
	v_lshlrev_b32_e32 v50, 16, v111
	v_and_b32_e32 v51, 0xffff0000, v111
	v_pk_mul_f32 v[46:47], v[66:67], v[46:47]
	v_cvt_pk_bf16_f32 v32, v32, v33
	v_cvt_pk_bf16_f32 v33, v34, v35
	v_cvt_pk_bf16_f32 v34, v36, v37
	v_add_co_u32_e32 v36, vcc, s62, v48
	v_pk_mul_f32 v[46:47], v[46:47], v[50:51]
	v_cvt_pk_bf16_f32 v35, v38, v39
	v_addc_co_u32_e32 v37, vcc, 0, v49, vcc
	global_store_dwordx4 v[36:37], v[32:35], off
	s_andn2_b64 vcc, exec, s[50:51]
	s_nop 0
	v_cvt_pk_bf16_f32 v32, v40, v41
	v_cvt_pk_bf16_f32 v33, v42, v43
	v_cvt_pk_bf16_f32 v34, v44, v45
	v_cvt_pk_bf16_f32 v35, v46, v47
	global_store_dwordx4 v[36:37], v[32:35], off offset:16
	s_cbranch_vccnz .LBB0_862
	s_cmp_gt_u32 s70, 29
	ds_write_b128 v176, v[88:91] offset:34816
	ds_write_b128 v177, v[96:99] offset:44032
	ds_write_b128 v178, v[100:103] offset:44032
	s_cbranch_scc1 .LBB0_862
	s_ashr_i32 s49, s48, 31
	s_lshl_b64 s[34:35], s[48:49], 13
	v_lshl_add_u64 v[32:33], v[160:161], 0, s[34:35]
	global_load_dwordx4 v[88:91], v[32:33], off
	v_add_u32_e32 v32, s47, v151
	v_add_u32_e32 v32, 0x80, v32
	v_add_u32_e32 v34, s47, v172
	v_mad_i64_i32 v[32:33], s[34:35], v32, s60, v[162:163]
	v_add_u32_e32 v34, 0x80, v34
	v_mad_i64_i32 v[34:35], s[34:35], v34, s60, v[162:163]
	global_load_dwordx4 v[96:99], v[32:33], off offset:2048
	global_load_dwordx4 v[100:103], v[34:35], off offset:2048
	s_branch .LBB0_862

.LBB0_1027:
	s_ashr_i32 s9, s16, 5
	s_lshl_b32 s17, s9, 6
	s_and_b32 s8, s3, 0xc0
	s_and_b32 s17, s17, 0xffffff00
	s_or_b32 s8, s8, s17
	s_lshl_b32 s9, s9, 8
	v_add_u32_e32 v0, s8, v14
	s_and_b32 s18, s9, 0x300
	v_mad_i64_i32 v[10:11], s[8:9], v0, s15, v[6:7]
	s_lshl_b32 s8, s13, 11
	v_or_b32_e32 v0, s18, v16
	s_and_b32 s8, s8, 0x70000
	v_lshl_or_b32 v4, v0, 11, s8
	v_lshl_add_u64 v[12:13], v[8:9], 0, v[4:5]
	v_mov_b32_e32 v176, v12
	v_mov_b32_e32 v177, v13
	v_mov_b32_e32 v178, v10
	v_mov_b32_e32 v179, v11
	s_lshl_b32 s8, s16, 3
	s_and_b32 s8, s8, 0xc0
	s_lshl_b32 s9, s16, 5
	s_add_i32 s17, s17, s8
	s_and_b32 s9, s9, 0xe0
	v_add_u32_e32 v10, s17, v14
	s_or_b32 s9, s18, s9
	v_ashrrev_i32_e32 v11, 31, v10
	v_or_b32_e32 v4, s9, v15
	v_lshlrev_b64 v[10:11], 11, v[10:11]
	v_lshl_or_b32 v10, v4, 1, v10
	v_lshl_add_u64 v[12:13], s[4:5], 0, v[10:11]
	v_lshl_add_u64 v[18:19], s[6:7], 0, v[10:11]
	global_load_dwordx2 v[12:13], v[12:13], off
	global_load_dwordx2 v[18:19], v[18:19], off
	v_lshl_add_u64 v[10:11], s[10:11], 0, v[10:11]
	v_readfirstlane_b32 s20, v170
	s_nop 3
	s_lshr_b32 s20, s20, 6
	s_and_b32 s21, s20, 1
	s_lshr_b32 s22, s20, 1
	s_lshl_b32 s23, s20, 8
	s_lshl_b32 s28, s21, 15
	s_sub_u32 s24, s23, s28
	s_subb_u32 s25, 0, 0
	s_mul_i32 s28, s22, 98304
	s_add_u32 s29, s23, 4096
	s_sub_u32 s26, s29, s28
	s_subb_u32 s27, 0, 0
	v_lshl_add_u64 v[172:173], v[176:177], 0, s[24:25]
	v_lshl_add_u64 v[84:85], v[178:179], 0, s[26:27]
	s_mov_b64 s[28:29], 0x8000
	v_lshl_add_u64 v[174:175], v[172:173], 0, s[28:29]
	s_mov_b64 s[28:29], 98304
	v_lshl_add_u64 v[86:87], v[84:85], 0, s[28:29]
	v_lshl_add_u64 v[88:89], v[86:87], 0, s[28:29]
	v_lshl_add_u64 v[90:91], v[88:89], 0, s[28:29]
	global_load_dwordx4 v[20:23], v[84:85], off offset:0
	global_load_dwordx4 v[24:27], v[86:87], off offset:0
	global_load_dwordx4 v[28:31], v[88:89], off offset:0
	global_load_dwordx4 v[32:35], v[90:91], off offset:0
	global_load_dwordx4 v[36:39], v[172:173], off offset:0
	global_load_dwordx4 v[40:43], v[174:175], off offset:0
	global_load_dwordx4 v[44:47], v[84:85], off offset:64
	global_load_dwordx4 v[48:51], v[86:87], off offset:64
	global_load_dwordx4 v[52:55], v[88:89], off offset:64
	global_load_dwordx4 v[56:59], v[90:91], off offset:64
	global_load_dwordx4 v[60:63], v[172:173], off offset:64
	global_load_dwordx4 v[64:67], v[174:175], off offset:64
	global_load_dwordx4 v[68:71], v[84:85], off offset:128
	global_load_dwordx4 v[72:75], v[86:87], off offset:128
	global_load_dwordx4 v[76:79], v[88:89], off offset:128
	global_load_dwordx4 v[80:83], v[90:91], off offset:128
	global_load_dwordx4 v[92:95], v[172:173], off offset:128
	global_load_dwordx4 v[96:99], v[174:175], off offset:128
	global_load_dwordx4 v[100:103], v[84:85], off offset:192
	global_load_dwordx4 v[104:107], v[86:87], off offset:192
	global_load_dwordx4 v[108:111], v[88:89], off offset:192
	global_load_dwordx4 v[112:115], v[90:91], off offset:192
	global_load_dwordx4 v[116:119], v[172:173], off offset:192
	global_load_dwordx4 v[120:123], v[174:175], off offset:192
	v_mov_b32_e32 v124, 0
	v_mov_b32_e32 v125, 0
	v_mov_b32_e32 v126, 0
	v_mov_b32_e32 v127, 0
	v_mov_b32_e32 v128, 0
	v_mov_b32_e32 v129, 0
	v_mov_b32_e32 v130, 0
	v_mov_b32_e32 v131, 0
	v_mov_b32_e32 v132, 0
	v_mov_b32_e32 v133, 0
	v_mov_b32_e32 v134, 0
	v_mov_b32_e32 v135, 0
	v_mov_b32_e32 v136, 0
	v_mov_b32_e32 v137, 0
	v_mov_b32_e32 v138, 0
	v_mov_b32_e32 v139, 0
	v_mov_b32_e32 v140, 0
	v_mov_b32_e32 v141, 0
	v_mov_b32_e32 v142, 0
	v_mov_b32_e32 v143, 0
	v_mov_b32_e32 v144, 0
	v_mov_b32_e32 v145, 0
	v_mov_b32_e32 v146, 0
	v_mov_b32_e32 v147, 0
	v_mov_b32_e32 v148, 0
	v_mov_b32_e32 v149, 0
	v_mov_b32_e32 v150, 0
	v_mov_b32_e32 v151, 0
	v_mov_b32_e32 v152, 0
	v_mov_b32_e32 v153, 0
	v_mov_b32_e32 v154, 0
	v_mov_b32_e32 v155, 0
	v_and_b32_e32 v156, 63, v170
	v_lshlrev_b32_e32 v156, 4, v156
	s_lshl_b32 s28, s20, 10
	v_add_u32_e32 v157, s28, v156
	s_lshl_b32 s28, s20, 13
	v_add_u32_e32 v158, s28, v156
	s_waitcnt vmcnt(18)
	v_mfma_f32_16x16x32_bf16 v[124:127], v[36:39], v[20:23], v[124:127]
	v_mfma_f32_16x16x32_bf16 v[128:131], v[40:43], v[20:23], v[128:131]
	v_mfma_f32_16x16x32_bf16 v[132:135], v[36:39], v[24:27], v[132:135]
	v_mfma_f32_16x16x32_bf16 v[136:139], v[40:43], v[24:27], v[136:139]
	v_mfma_f32_16x16x32_bf16 v[140:143], v[36:39], v[28:31], v[140:143]
	v_mfma_f32_16x16x32_bf16 v[144:147], v[40:43], v[28:31], v[144:147]
	v_mfma_f32_16x16x32_bf16 v[148:151], v[36:39], v[32:35], v[148:151]
	v_mfma_f32_16x16x32_bf16 v[152:155], v[40:43], v[32:35], v[152:155]
	s_waitcnt vmcnt(12)
	v_mfma_f32_16x16x32_bf16 v[124:127], v[60:63], v[44:47], v[124:127]
	v_mfma_f32_16x16x32_bf16 v[128:131], v[64:67], v[44:47], v[128:131]
	v_mfma_f32_16x16x32_bf16 v[132:135], v[60:63], v[48:51], v[132:135]
	v_mfma_f32_16x16x32_bf16 v[136:139], v[64:67], v[48:51], v[136:139]
	v_mfma_f32_16x16x32_bf16 v[140:143], v[60:63], v[52:55], v[140:143]
	v_mfma_f32_16x16x32_bf16 v[144:147], v[64:67], v[52:55], v[144:147]
	v_mfma_f32_16x16x32_bf16 v[148:151], v[60:63], v[56:59], v[148:151]
	v_mfma_f32_16x16x32_bf16 v[152:155], v[64:67], v[56:59], v[152:155]
	s_waitcnt vmcnt(6)
	v_mfma_f32_16x16x32_bf16 v[124:127], v[92:95], v[68:71], v[124:127]
	v_mfma_f32_16x16x32_bf16 v[128:131], v[96:99], v[68:71], v[128:131]
	v_mfma_f32_16x16x32_bf16 v[132:135], v[92:95], v[72:75], v[132:135]
	v_mfma_f32_16x16x32_bf16 v[136:139], v[96:99], v[72:75], v[136:139]
	v_mfma_f32_16x16x32_bf16 v[140:143], v[92:95], v[76:79], v[140:143]
	v_mfma_f32_16x16x32_bf16 v[144:147], v[96:99], v[76:79], v[144:147]
	v_mfma_f32_16x16x32_bf16 v[148:151], v[92:95], v[80:83], v[148:151]
	v_mfma_f32_16x16x32_bf16 v[152:155], v[96:99], v[80:83], v[152:155]
	s_waitcnt vmcnt(0)
	v_mfma_f32_16x16x32_bf16 v[124:127], v[116:119], v[100:103], v[124:127]
	v_mfma_f32_16x16x32_bf16 v[128:131], v[120:123], v[100:103], v[128:131]
	v_mfma_f32_16x16x32_bf16 v[132:135], v[116:119], v[104:107], v[132:135]
	v_mfma_f32_16x16x32_bf16 v[136:139], v[120:123], v[104:107], v[136:139]
	v_mfma_f32_16x16x32_bf16 v[140:143], v[116:119], v[108:111], v[140:143]
	v_mfma_f32_16x16x32_bf16 v[144:147], v[120:123], v[108:111], v[144:147]
	v_mfma_f32_16x16x32_bf16 v[148:151], v[116:119], v[112:115], v[148:151]
	v_mfma_f32_16x16x32_bf16 v[152:155], v[120:123], v[112:115], v[152:155]
	s_nop 8
	ds_write_b128 v157, v[124:127] offset:0
	ds_write_b128 v157, v[128:131] offset:8192
	ds_write_b128 v157, v[132:135] offset:16384
	ds_write_b128 v157, v[136:139] offset:24576
	ds_write_b128 v157, v[140:143] offset:32768
	ds_write_b128 v157, v[144:147] offset:40960
	ds_write_b128 v157, v[148:151] offset:49152
	ds_write_b128 v157, v[152:155] offset:57344
	s_waitcnt lgkmcnt(0)
	s_barrier
	ds_read_b128 v[20:23], v158 offset:0
	ds_read_b128 v[24:27], v158 offset:1024
	ds_read_b128 v[28:31], v158 offset:2048
	ds_read_b128 v[32:35], v158 offset:3072
	ds_read_b128 v[36:39], v158 offset:4096
	ds_read_b128 v[40:43], v158 offset:5120
	ds_read_b128 v[44:47], v158 offset:6144
	ds_read_b128 v[48:51], v158 offset:7168
	s_waitcnt lgkmcnt(0)
	v_pk_add_f32 v[0:1], v[20:21], v[24:25]
	v_pk_add_f32 v[2:3], v[22:23], v[26:27]
	v_pk_add_f32 v[0:1], v[0:1], v[28:29]
	v_pk_add_f32 v[2:3], v[2:3], v[30:31]
	v_pk_add_f32 v[0:1], v[0:1], v[32:33]
	v_pk_add_f32 v[2:3], v[2:3], v[34:35]
	v_pk_add_f32 v[0:1], v[0:1], v[36:37]
	v_pk_add_f32 v[2:3], v[2:3], v[38:39]
	v_pk_add_f32 v[0:1], v[0:1], v[40:41]
	v_pk_add_f32 v[2:3], v[2:3], v[42:43]
	v_pk_add_f32 v[0:1], v[0:1], v[44:45]
	v_pk_add_f32 v[2:3], v[2:3], v[46:47]
	v_pk_add_f32 v[0:1], v[0:1], v[48:49]
	v_pk_add_f32 v[2:3], v[2:3], v[50:51]
	s_add_i32 s16, s16, s30
	s_add_i32 s3, s3, s12
	s_add_i32 s13, s13, s14
	s_cmpk_gt_i32 s16, 0xff
	s_waitcnt vmcnt(0)
	v_lshlrev_b32_e32 v20, 16, v12
	v_and_b32_e32 v21, 0xffff0000, v12
	v_lshlrev_b32_e32 v22, 16, v18
	v_and_b32_e32 v23, 0xffff0000, v18
	v_lshlrev_b32_e32 v12, 16, v13
	v_and_b32_e32 v13, 0xffff0000, v13
	v_lshlrev_b32_e32 v18, 16, v19
	v_and_b32_e32 v19, 0xffff0000, v19
	v_pk_fma_f32 v[0:1], v[0:1], v[22:23], v[20:21]
	v_pk_fma_f32 v[2:3], v[2:3], v[18:19], v[12:13]
	v_cvt_pk_bf16_f32 v0, v0, v1
	v_cvt_pk_bf16_f32 v1, v2, v3
	global_store_dwordx2 v[10:11], v[0:1], off
	s_cbranch_scc0 .LBB0_1027

.LBB0_1130:
	s_ashr_i32 s13, s18, 5
	s_lshl_b32 s19, s13, 6
	s_lshl_b32 s13, s13, 8
	s_and_b32 s12, s16, 0xc0
	s_and_b32 s20, s19, 0xffffff00
	s_and_b32 s19, s13, 0x300
	s_lshl_b32 s13, s14, 11
	v_or_b32_e32 v0, s19, v17
	s_and_b32 s13, s13, 0x70000
	s_or_b32 s12, s12, s20
	v_lshl_or_b32 v4, v0, 11, s13
	v_add_u32_e32 v0, s12, v18
	v_ashrrev_i32_e32 v1, 31, v0
	v_lshlrev_b64 v[0:1], 11, v[0:1]
	v_lshl_add_u64 v[10:11], v[6:7], 0, v[4:5]
	v_lshl_add_u64 v[12:13], v[8:9], 0, v[0:1]
	v_mov_b32_e32 v176, v10
	v_mov_b32_e32 v177, v11
	v_mov_b32_e32 v178, v12
	v_mov_b32_e32 v179, v13
	s_lshl_b32 s12, s18, 3
	s_and_b32 s12, s12, 0xc0
	s_add_i32 s20, s20, s12
	v_add_u32_e32 v4, s20, v15
	v_or_b32_e32 v10, v4, v14
	s_lshl_b32 s12, s18, 5
	v_ashrrev_i32_e32 v11, 31, v10
	s_and_b32 s12, s12, 0xe0
	v_lshlrev_b64 v[20:21], 12, v[10:11]
	s_or_b32 s12, s19, s12
	v_lshl_add_u64 v[12:13], s[6:7], 0, v[20:21]
	v_or_b32_e32 v19, s12, v16
	v_lshl_add_u64 v[10:11], s[4:5], 0, v[20:21]
	v_lshl_add_u64 v[12:13], v[12:13], 0, s[10:11]
	v_cmp_gt_u32_e32 vcc, s3, v4
	v_lshlrev_b32_e32 v4, 2, v19
	s_nop 1
	v_cndmask_b32_e32 v11, v13, v11, vcc
	v_cndmask_b32_e32 v10, v12, v10, vcc
	v_lshl_add_u64 v[10:11], v[10:11], 0, v[4:5]
	global_load_dwordx4 v[10:13], v[10:11], off
	v_lshl_add_u64 v[20:21], s[8:9], 0, v[20:21]
	v_lshl_add_u64 v[20:21], v[20:21], 0, v[4:5]
	v_readfirstlane_b32 s20, v170
	s_nop 3
	s_lshr_b32 s20, s20, 6
	s_and_b32 s21, s20, 1
	s_lshr_b32 s22, s20, 1
	s_lshl_b32 s23, s20, 8
	s_lshl_b32 s28, s21, 15
	s_sub_u32 s24, s23, s28
	s_subb_u32 s25, 0, 0
	s_mul_i32 s28, s22, 32768
	s_add_u32 s29, s23, 0
	s_sub_u32 s26, s29, s28
	s_subb_u32 s27, 0, 0
	v_lshl_add_u64 v[172:173], v[176:177], 0, s[24:25]
	v_lshl_add_u64 v[84:85], v[178:179], 0, s[26:27]
	s_mov_b64 s[28:29], 0x8000
	v_lshl_add_u64 v[174:175], v[172:173], 0, s[28:29]
	s_mov_b64 s[28:29], 32768
	v_lshl_add_u64 v[86:87], v[84:85], 0, s[28:29]
	v_lshl_add_u64 v[88:89], v[86:87], 0, s[28:29]
	v_lshl_add_u64 v[90:91], v[88:89], 0, s[28:29]
	global_load_dwordx4 v[24:27], v[84:85], off offset:0
	global_load_dwordx4 v[28:31], v[86:87], off offset:0
	global_load_dwordx4 v[32:35], v[88:89], off offset:0
	global_load_dwordx4 v[36:39], v[90:91], off offset:0
	global_load_dwordx4 v[40:43], v[172:173], off offset:0
	global_load_dwordx4 v[44:47], v[174:175], off offset:0
	global_load_dwordx4 v[48:51], v[84:85], off offset:64
	global_load_dwordx4 v[52:55], v[86:87], off offset:64
	global_load_dwordx4 v[56:59], v[88:89], off offset:64
	global_load_dwordx4 v[60:63], v[90:91], off offset:64
	global_load_dwordx4 v[64:67], v[172:173], off offset:64
	global_load_dwordx4 v[68:71], v[174:175], off offset:64
	global_load_dwordx4 v[72:75], v[84:85], off offset:128
	global_load_dwordx4 v[76:79], v[86:87], off offset:128
	global_load_dwordx4 v[80:83], v[88:89], off offset:128
	global_load_dwordx4 v[92:95], v[90:91], off offset:128
	global_load_dwordx4 v[96:99], v[172:173], off offset:128
	global_load_dwordx4 v[100:103], v[174:175], off offset:128
	global_load_dwordx4 v[104:107], v[84:85], off offset:192
	global_load_dwordx4 v[108:111], v[86:87], off offset:192
	global_load_dwordx4 v[112:115], v[88:89], off offset:192
	global_load_dwordx4 v[116:119], v[90:91], off offset:192
	global_load_dwordx4 v[120:123], v[172:173], off offset:192
	global_load_dwordx4 v[124:127], v[174:175], off offset:192
	v_mov_b32_e32 v128, 0
	v_mov_b32_e32 v129, 0
	v_mov_b32_e32 v130, 0
	v_mov_b32_e32 v131, 0
	v_mov_b32_e32 v132, 0
	v_mov_b32_e32 v133, 0
	v_mov_b32_e32 v134, 0
	v_mov_b32_e32 v135, 0
	v_mov_b32_e32 v136, 0
	v_mov_b32_e32 v137, 0
	v_mov_b32_e32 v138, 0
	v_mov_b32_e32 v139, 0
	v_mov_b32_e32 v140, 0
	v_mov_b32_e32 v141, 0
	v_mov_b32_e32 v142, 0
	v_mov_b32_e32 v143, 0
	v_mov_b32_e32 v144, 0
	v_mov_b32_e32 v145, 0
	v_mov_b32_e32 v146, 0
	v_mov_b32_e32 v147, 0
	v_mov_b32_e32 v148, 0
	v_mov_b32_e32 v149, 0
	v_mov_b32_e32 v150, 0
	v_mov_b32_e32 v151, 0
	v_mov_b32_e32 v152, 0
	v_mov_b32_e32 v153, 0
	v_mov_b32_e32 v154, 0
	v_mov_b32_e32 v155, 0
	v_mov_b32_e32 v156, 0
	v_mov_b32_e32 v157, 0
	v_mov_b32_e32 v158, 0
	v_mov_b32_e32 v159, 0
	v_and_b32_e32 v160, 63, v170
	v_lshlrev_b32_e32 v160, 4, v160
	s_lshl_b32 s28, s20, 10
	v_add_u32_e32 v161, s28, v160
	s_lshl_b32 s28, s20, 13
	v_add_u32_e32 v162, s28, v160
	s_waitcnt vmcnt(18)
	v_mfma_f32_16x16x32_bf16 v[128:131], v[40:43], v[24:27], v[128:131]
	v_mfma_f32_16x16x32_bf16 v[132:135], v[44:47], v[24:27], v[132:135]
	v_mfma_f32_16x16x32_bf16 v[136:139], v[40:43], v[28:31], v[136:139]
	v_mfma_f32_16x16x32_bf16 v[140:143], v[44:47], v[28:31], v[140:143]
	v_mfma_f32_16x16x32_bf16 v[144:147], v[40:43], v[32:35], v[144:147]
	v_mfma_f32_16x16x32_bf16 v[148:151], v[44:47], v[32:35], v[148:151]
	v_mfma_f32_16x16x32_bf16 v[152:155], v[40:43], v[36:39], v[152:155]
	v_mfma_f32_16x16x32_bf16 v[156:159], v[44:47], v[36:39], v[156:159]
	s_waitcnt vmcnt(12)
	v_mfma_f32_16x16x32_bf16 v[128:131], v[64:67], v[48:51], v[128:131]
	v_mfma_f32_16x16x32_bf16 v[132:135], v[68:71], v[48:51], v[132:135]
	v_mfma_f32_16x16x32_bf16 v[136:139], v[64:67], v[52:55], v[136:139]
	v_mfma_f32_16x16x32_bf16 v[140:143], v[68:71], v[52:55], v[140:143]
	v_mfma_f32_16x16x32_bf16 v[144:147], v[64:67], v[56:59], v[144:147]
	v_mfma_f32_16x16x32_bf16 v[148:151], v[68:71], v[56:59], v[148:151]
	v_mfma_f32_16x16x32_bf16 v[152:155], v[64:67], v[60:63], v[152:155]
	v_mfma_f32_16x16x32_bf16 v[156:159], v[68:71], v[60:63], v[156:159]
	s_waitcnt vmcnt(6)
	v_mfma_f32_16x16x32_bf16 v[128:131], v[96:99], v[72:75], v[128:131]
	v_mfma_f32_16x16x32_bf16 v[132:135], v[100:103], v[72:75], v[132:135]
	v_mfma_f32_16x16x32_bf16 v[136:139], v[96:99], v[76:79], v[136:139]
	v_mfma_f32_16x16x32_bf16 v[140:143], v[100:103], v[76:79], v[140:143]
	v_mfma_f32_16x16x32_bf16 v[144:147], v[96:99], v[80:83], v[144:147]
	v_mfma_f32_16x16x32_bf16 v[148:151], v[100:103], v[80:83], v[148:151]
	v_mfma_f32_16x16x32_bf16 v[152:155], v[96:99], v[92:95], v[152:155]
	v_mfma_f32_16x16x32_bf16 v[156:159], v[100:103], v[92:95], v[156:159]
	s_waitcnt vmcnt(0)
	v_mfma_f32_16x16x32_bf16 v[128:131], v[120:123], v[104:107], v[128:131]
	v_mfma_f32_16x16x32_bf16 v[132:135], v[124:127], v[104:107], v[132:135]
	v_mfma_f32_16x16x32_bf16 v[136:139], v[120:123], v[108:111], v[136:139]
	v_mfma_f32_16x16x32_bf16 v[140:143], v[124:127], v[108:111], v[140:143]
	v_mfma_f32_16x16x32_bf16 v[144:147], v[120:123], v[112:115], v[144:147]
	v_mfma_f32_16x16x32_bf16 v[148:151], v[124:127], v[112:115], v[148:151]
	v_mfma_f32_16x16x32_bf16 v[152:155], v[120:123], v[116:119], v[152:155]
	v_mfma_f32_16x16x32_bf16 v[156:159], v[124:127], v[116:119], v[156:159]
	s_nop 8
	ds_write_b128 v161, v[128:131] offset:0
	ds_write_b128 v161, v[132:135] offset:8192
	ds_write_b128 v161, v[136:139] offset:16384
	ds_write_b128 v161, v[140:143] offset:24576
	ds_write_b128 v161, v[144:147] offset:32768
	ds_write_b128 v161, v[148:151] offset:40960
	ds_write_b128 v161, v[152:155] offset:49152
	ds_write_b128 v161, v[156:159] offset:57344
	s_waitcnt lgkmcnt(0)
	s_barrier
	ds_read_b128 v[24:27], v162 offset:0
	ds_read_b128 v[28:31], v162 offset:1024
	ds_read_b128 v[32:35], v162 offset:2048
	ds_read_b128 v[36:39], v162 offset:3072
	ds_read_b128 v[40:43], v162 offset:4096
	ds_read_b128 v[44:47], v162 offset:5120
	ds_read_b128 v[48:51], v162 offset:6144
	ds_read_b128 v[52:55], v162 offset:7168
	s_waitcnt lgkmcnt(0)
	v_pk_add_f32 v[0:1], v[24:25], v[28:29]
	v_pk_add_f32 v[2:3], v[26:27], v[30:31]
	v_pk_add_f32 v[0:1], v[0:1], v[32:33]
	v_pk_add_f32 v[2:3], v[2:3], v[34:35]
	v_pk_add_f32 v[0:1], v[0:1], v[36:37]
	v_pk_add_f32 v[2:3], v[2:3], v[38:39]
	v_pk_add_f32 v[0:1], v[0:1], v[40:41]
	v_pk_add_f32 v[2:3], v[2:3], v[42:43]
	v_pk_add_f32 v[0:1], v[0:1], v[44:45]
	v_pk_add_f32 v[2:3], v[2:3], v[46:47]
	v_pk_add_f32 v[0:1], v[0:1], v[48:49]
	v_pk_add_f32 v[2:3], v[2:3], v[50:51]
	v_pk_add_f32 v[0:1], v[0:1], v[52:53]
	v_pk_add_f32 v[2:3], v[2:3], v[54:55]
	s_add_i32 s18, s18, s30
	s_add_i32 s14, s14, s15
	s_add_i32 s16, s16, s17
	s_cmpk_gt_i32 s18, 0xff
	s_waitcnt vmcnt(0)
	v_pk_add_f32 v[2:3], v[2:3], v[12:13]
	v_pk_add_f32 v[0:1], v[0:1], v[10:11]
	global_store_dwordx4 v[20:21], v[0:3], off
	s_cbranch_scc0 .LBB0_1130
